# v27 + accumulator-clearing MFMAs of every GEMM prologue moved behind the K-tile 1 DMA pieces (first K-tiles requested earlier, clears run under the DMA latency)
# baseline (speedup 1.0000x reference)
.LBB0_105:
	v_mov_b32_e32 v165, v27
	v_lshl_add_u64 v[58:59], s[86:87], 0, v[164:165]
	v_mov_b32_e32 v161, v27
	v_lshl_add_u64 v[84:85], s[86:87], 0, v[160:161]
	s_add_i32 m0, s17, 0x18000
	v_lshl_add_u64 v[58:59], v[58:59], 0, s[82:83]
	v_readlane_b32 s26, v251, 55
	v_mov_b32_e32 v167, v27
	global_load_lds_dwordx4 v[58:59], off
	v_lshl_add_u64 v[58:59], v[84:85], 0, s[82:83]
	s_add_i32 m0, s17, 0x1a000
	v_readlane_b32 s27, v251, 56
	s_add_i32 s22, s17, 0x8000
	v_mov_b32_e32 v163, v27
	global_load_lds_dwordx4 v[58:59], off
	v_lshl_add_u64 v[58:59], s[26:27], 0, v[166:167]
	s_mov_b32 m0, s22
	s_add_i32 s80, s17, 0xa000
	global_load_lds_dwordx4 v[58:59], off
	v_lshl_add_u64 v[58:59], s[26:27], 0, v[162:163]
	s_mov_b32 m0, s80
	s_and_b32 s1, s1, 3
	global_load_lds_dwordx4 v[58:59], off
	s_add_i32 m0, s17, 0x1c000
	v_lshl_add_u64 v[58:59], s[52:53], 0, v[164:165]
	global_load_lds_dwordx4 v[58:59], off
	v_lshl_add_u64 v[58:59], s[52:53], 0, v[160:161]
	s_add_i32 m0, s17, 0x1e000
	v_mul_lo_u32 v26, v26, s7
	global_load_lds_dwordx4 v[58:59], off
	v_mov_b32_e32 v242, 0
	v_mov_b32_e32 v243, 0
	v_mov_b32_e32 v244, 0
	v_mov_b32_e32 v245, 0
	s_nop 1
	v_mfma_f32_16x16x32_bf16 v[148:151], v[242:245], v[242:245], 0
	v_mfma_f32_16x16x32_bf16 v[152:155], v[242:245], v[242:245], 0
	v_mfma_f32_16x16x32_bf16 v[128:131], v[242:245], v[242:245], 0
	v_mfma_f32_16x16x32_bf16 v[132:135], v[242:245], v[242:245], 0
	v_mfma_f32_16x16x32_bf16 v[108:111], v[242:245], v[242:245], 0
	v_mfma_f32_16x16x32_bf16 v[112:115], v[242:245], v[242:245], 0
	v_mfma_f32_16x16x32_bf16 v[88:91], v[242:245], v[242:245], 0
	v_mfma_f32_16x16x32_bf16 v[92:95], v[242:245], v[242:245], 0
	v_mfma_f32_16x16x32_bf16 v[140:143], v[242:245], v[242:245], 0
	v_mfma_f32_16x16x32_bf16 v[136:139], v[242:245], v[242:245], 0
	v_mfma_f32_16x16x32_bf16 v[120:123], v[242:245], v[242:245], 0
	v_mfma_f32_16x16x32_bf16 v[116:119], v[242:245], v[242:245], 0
	v_mfma_f32_16x16x32_bf16 v[100:103], v[242:245], v[242:245], 0
	v_mfma_f32_16x16x32_bf16 v[96:99], v[242:245], v[242:245], 0
	v_mfma_f32_16x16x32_bf16 v[80:83], v[242:245], v[242:245], 0
	v_mfma_f32_16x16x32_bf16 v[76:79], v[242:245], v[242:245], 0
	v_mfma_f32_16x16x32_bf16 v[68:71], v[242:245], v[242:245], 0
	v_mfma_f32_16x16x32_bf16 v[72:75], v[242:245], v[242:245], 0
	v_mfma_f32_16x16x32_bf16 v[48:51], v[242:245], v[242:245], 0
	v_mfma_f32_16x16x32_bf16 v[52:55], v[242:245], v[242:245], 0
	v_mfma_f32_16x16x32_bf16 v[28:31], v[242:245], v[242:245], 0
	v_mfma_f32_16x16x32_bf16 v[32:35], v[242:245], v[242:245], 0
	v_mfma_f32_16x16x32_bf16 v[10:13], v[242:245], v[242:245], 0
	v_mfma_f32_16x16x32_bf16 v[14:17], v[242:245], v[242:245], 0
	v_mfma_f32_16x16x32_bf16 v[64:67], v[242:245], v[242:245], 0
	v_mfma_f32_16x16x32_bf16 v[60:63], v[242:245], v[242:245], 0
	v_mfma_f32_16x16x32_bf16 v[44:47], v[242:245], v[242:245], 0
	v_mfma_f32_16x16x32_bf16 v[40:43], v[242:245], v[242:245], 0
	v_mfma_f32_16x16x32_bf16 v[22:25], v[242:245], v[242:245], 0
	v_mfma_f32_16x16x32_bf16 v[18:21], v[242:245], v[242:245], 0
	v_mfma_f32_16x16x32_bf16 v[2:5], v[242:245], v[242:245], 0
	v_mfma_f32_16x16x32_bf16 v[6:9], v[242:245], v[242:245], 0
	s_waitcnt vmcnt(8)
	s_barrier
	v_bfe_u32 v59, v37, 4, 2
	v_and_b32_e32 v58, 15, v37
	v_lshlrev_b32_e32 v185, 4, v59
	v_lshlrev_b32_e32 v37, 2, v37
	v_lshl_or_b32 v184, s11, 6, v58
	v_lshl_or_b32 v58, v58, 6, v185
	s_lshl_b32 s11, s11, 13
	v_and_b32_e32 v37, 32, v37
	v_bitop3_b32 v84, v58, s11, v37 bitop3:0xde
	s_lshl_b32 s11, s1, 12
	v_bitop3_b32 v186, v58, s11, v37 bitop3:0xde
	s_cmpk_lt_u32 s0, 0x100
	v_lshrrev_b32_e32 v37, 1, v56
	v_mul_lo_u32 v58, v39, s7
	s_mov_b32 s11, 0x2c000
	s_cselect_b64 s[60:61], -1, 0
	v_cmp_eq_u32_e64 s[38:39], 0, v59
	s_lshl_b32 s26, s1, 1
	v_lshl_or_b32 v187, s1, 6, v185
	v_mad_u64_u32 v[58:59], s[0:1], v37, s11, v[58:59]
	v_and_b32_e32 v37, 1, v56
	v_lshl_or_b32 v37, v37, 6, v58
	v_lshl_add_u32 v176, v57, 1, v37
	v_lshrrev_b32_e32 v37, 1, v36
	v_mad_u64_u32 v[56:57], s[0:1], v37, s11, v[26:27]
	s_waitcnt vmcnt(6)
	v_and_b32_e32 v26, 1, v36
	v_readlane_b32 s0, v251, 36
	v_lshl_or_b32 v26, v26, 6, v56
	s_mov_b32 s94, s0
	v_readlane_b32 s0, v251, 34
	v_readlane_b32 s78, v251, 37
	s_mov_b32 s81, 0
	s_orn2_b32 s26, s26, 47
	v_mov_b32_e32 v177, v27
	v_lshl_add_u32 v178, v38, 1, v26
	v_mov_b32_e32 v179, v27
	v_add_u32_e32 v188, 0, v84
	v_readlane_b32 s31, v251, 35
	s_mov_b32 s30, s0
	s_mov_b64 s[76:77], s[86:87]
	v_readlane_b32 s79, v251, 38
	s_barrier
	s_mov_b32 s98, 0
	s_branch .LBB0_108

.LBB0_202:
	v_mov_b32_e32 v159, v27
	v_lshl_add_u64 v[10:11], s[36:37], 0, v[158:159]
	v_mov_b32_e32 v163, v27
	v_lshl_add_u64 v[12:13], s[36:37], 0, v[162:163]
	v_mov_b32_e32 v157, v27
	s_add_i32 m0, s11, 0x18000
	v_lshl_add_u64 v[10:11], v[10:11], 0, s[82:83]
	v_lshl_add_u64 v[14:15], s[70:71], 0, v[156:157]
	v_mov_b32_e32 v161, v27
	global_load_lds_dwordx4 v[10:11], off
	v_lshl_add_u64 v[10:11], v[12:13], 0, s[82:83]
	s_add_i32 m0, s11, 0x1a000
	s_add_i32 s26, s11, 0x8000
	v_lshl_add_u64 v[16:17], s[70:71], 0, v[160:161]
	global_load_lds_dwordx4 v[10:11], off
	v_lshl_add_u64 v[10:11], v[14:15], 0, s[82:83]
	s_mov_b32 m0, s26
	s_add_i32 s27, s11, 0xa000
	global_load_lds_dwordx4 v[10:11], off
	v_lshl_add_u64 v[10:11], v[16:17], 0, s[82:83]
	s_mov_b32 m0, s27
	v_and_b32_e32 v9, 15, v2
	global_load_lds_dwordx4 v[10:11], off
	s_add_i32 m0, s11, 0x1c000
	v_lshl_add_u64 v[10:11], s[28:29], 0, v[158:159]
	global_load_lds_dwordx4 v[10:11], off
	v_lshl_add_u64 v[10:11], s[28:29], 0, v[162:163]
	s_add_i32 m0, s11, 0x1e000
	v_and_b32_e32 v187, 48, v2
	global_load_lds_dwordx4 v[10:11], off
	v_mov_b32_e32 v242, 0
	v_mov_b32_e32 v243, 0
	v_mov_b32_e32 v244, 0
	v_mov_b32_e32 v245, 0
	s_nop 1
	v_mfma_f32_16x16x32_bf16 v[148:151], v[242:245], v[242:245], 0
	v_mfma_f32_16x16x32_bf16 v[152:155], v[242:245], v[242:245], 0
	v_mfma_f32_16x16x32_bf16 v[124:127], v[242:245], v[242:245], 0
	v_mfma_f32_16x16x32_bf16 v[128:131], v[242:245], v[242:245], 0
	v_mfma_f32_16x16x32_bf16 v[108:111], v[242:245], v[242:245], 0
	v_mfma_f32_16x16x32_bf16 v[112:115], v[242:245], v[242:245], 0
	v_mfma_f32_16x16x32_bf16 v[92:95], v[242:245], v[242:245], 0
	v_mfma_f32_16x16x32_bf16 v[96:99], v[242:245], v[242:245], 0
	v_mfma_f32_16x16x32_bf16 v[140:143], v[242:245], v[242:245], 0
	v_mfma_f32_16x16x32_bf16 v[144:147], v[242:245], v[242:245], 0
	v_mfma_f32_16x16x32_bf16 v[132:135], v[242:245], v[242:245], 0
	v_mfma_f32_16x16x32_bf16 v[136:139], v[242:245], v[242:245], 0
	v_mfma_f32_16x16x32_bf16 v[116:119], v[242:245], v[242:245], 0
	v_mfma_f32_16x16x32_bf16 v[120:123], v[242:245], v[242:245], 0
	v_mfma_f32_16x16x32_bf16 v[100:103], v[242:245], v[242:245], 0
	v_mfma_f32_16x16x32_bf16 v[104:107], v[242:245], v[242:245], 0
	v_mfma_f32_16x16x32_bf16 v[76:79], v[242:245], v[242:245], 0
	v_mfma_f32_16x16x32_bf16 v[80:83], v[242:245], v[242:245], 0
	v_mfma_f32_16x16x32_bf16 v[60:63], v[242:245], v[242:245], 0
	v_mfma_f32_16x16x32_bf16 v[64:67], v[242:245], v[242:245], 0
	v_mfma_f32_16x16x32_bf16 v[44:47], v[242:245], v[242:245], 0
	v_mfma_f32_16x16x32_bf16 v[48:51], v[242:245], v[242:245], 0
	v_mfma_f32_16x16x32_bf16 v[28:31], v[242:245], v[242:245], 0
	v_mfma_f32_16x16x32_bf16 v[32:35], v[242:245], v[242:245], 0
	v_mfma_f32_16x16x32_bf16 v[84:87], v[242:245], v[242:245], 0
	v_mfma_f32_16x16x32_bf16 v[88:91], v[242:245], v[242:245], 0
	v_mfma_f32_16x16x32_bf16 v[68:71], v[242:245], v[242:245], 0
	v_mfma_f32_16x16x32_bf16 v[72:75], v[242:245], v[242:245], 0
	v_mfma_f32_16x16x32_bf16 v[52:55], v[242:245], v[242:245], 0
	v_mfma_f32_16x16x32_bf16 v[56:59], v[242:245], v[242:245], 0
	v_mfma_f32_16x16x32_bf16 v[36:39], v[242:245], v[242:245], 0
	v_mfma_f32_16x16x32_bf16 v[40:43], v[242:245], v[242:245], 0
	s_waitcnt vmcnt(8)
	s_barrier
	v_lshlrev_b32_e32 v10, 2, v2
	v_lshlrev_b32_e32 v2, 3, v2
	v_and_b32_e32 v164, 0x1f8, v2
	v_lshlrev_b32_e32 v2, 13, v3
	v_and_b32_e32 v2, 0xffffc000, v2
	v_lshl_add_u32 v2, v4, 10, v2
	v_and_b32_e32 v3, 1, v3
	s_and_b32 s39, s31, 3
	v_lshl_or_b32 v188, s38, 6, v9
	s_lshl_b32 s31, s38, 13
	v_lshl_or_b32 v9, v9, 6, v187
	v_and_b32_e32 v10, 32, v10
	v_lshl_or_b32 v2, v3, 6, v2
	v_bitop3_b32 v11, v9, s31, v10 bitop3:0xde
	s_lshl_b32 s31, s39, 12
	v_lshl_add_u32 v166, v5, 1, v2
	v_lshlrev_b32_e32 v2, 13, v6
	s_cmpk_lt_u32 s30, 0x100
	v_and_b32_e32 v2, 0xffffc000, v2
	v_bitop3_b32 v189, v9, s31, v10 bitop3:0xde
	s_waitcnt vmcnt(6)
	s_cselect_b64 s[30:31], -1, 0
	s_lshl_b32 s38, s38, 15
	s_lshl_b32 s39, s39, 13
	v_lshl_add_u32 v2, v7, 10, v2
	v_and_b32_e32 v3, 1, v6
	s_or_b32 s46, s39, s38
	v_lshl_or_b32 v2, v3, 6, v2
	v_readlane_b32 s4, v252, 16
	v_readlane_b32 s40, v250, 11
	s_ashr_i32 s47, s46, 31
	v_mov_b32_e32 v165, v27
	v_mov_b32_e32 v167, v27
	v_lshl_add_u32 v176, v8, 1, v2
	v_mov_b32_e32 v177, v27
	s_mov_b64 s[60:61], 0
	v_add_u32_e32 v190, 0, v11
	s_mov_b32 s58, s4
	v_readlane_b32 s41, v250, 12
	v_readlane_b32 s59, v252, 17
	s_mov_b64 s[78:79], s[70:71]
	s_mov_b64 s[76:77], s[36:37]
	s_barrier
	s_branch .LBB0_205

.LBB0_377:
	v_mov_b32_e32 v159, v27
	v_lshl_add_u64 v[2:3], s[20:21], 0, v[158:159]
	v_mov_b32_e32 v163, v27
	v_readlane_b32 s52, v253, 57
	v_lshl_add_u64 v[4:5], s[20:21], 0, v[162:163]
	v_mov_b32_e32 v157, v27
	v_readlane_b32 s53, v253, 58
	s_and_b32 s1, s1, 3
	s_add_i32 m0, s11, 0x18000
	v_lshl_add_u64 v[2:3], v[2:3], 0, s[82:83]
	v_lshl_add_u64 v[14:15], s[52:53], 0, v[156:157]
	v_mov_b32_e32 v161, v27
	s_lshl_b32 s12, s27, 13
	s_lshl_b32 s34, s1, 12
	global_load_lds_dwordx4 v[2:3], off
	v_lshl_add_u64 v[2:3], v[4:5], 0, s[82:83]
	s_add_i32 m0, s11, 0x1a000
	s_add_i32 s23, s11, 0x8000
	s_add_i32 s26, s11, 0xa000
	v_lshl_add_u64 v[16:17], s[52:53], 0, v[160:161]
	global_load_lds_dwordx4 v[2:3], off
	v_lshl_add_u64 v[2:3], v[14:15], 0, s[82:83]
	s_mov_b32 m0, s23
	s_add_u32 s30, s20, 0x20080
	global_load_lds_dwordx4 v[2:3], off
	v_lshl_add_u64 v[2:3], v[16:17], 0, s[82:83]
	s_mov_b32 m0, s26
	s_addc_u32 s31, s21, 0
	global_load_lds_dwordx4 v[2:3], off
	s_add_i32 m0, s11, 0x1c000
	v_lshl_add_u64 v[2:3], s[30:31], 0, v[158:159]
	global_load_lds_dwordx4 v[2:3], off
	v_lshl_add_u64 v[2:3], s[30:31], 0, v[162:163]
	s_add_i32 m0, s11, 0x1e000
	v_and_b32_e32 v188, 48, v6
	global_load_lds_dwordx4 v[2:3], off
	v_mov_b32_e32 v242, 0
	v_mov_b32_e32 v243, 0
	v_mov_b32_e32 v244, 0
	v_mov_b32_e32 v245, 0
	s_nop 1
	v_mfma_f32_16x16x32_bf16 v[140:143], v[242:245], v[242:245], 0
	v_mfma_f32_16x16x32_bf16 v[144:147], v[242:245], v[242:245], 0
	v_mfma_f32_16x16x32_bf16 v[124:127], v[242:245], v[242:245], 0
	v_mfma_f32_16x16x32_bf16 v[128:131], v[242:245], v[242:245], 0
	v_mfma_f32_16x16x32_bf16 v[108:111], v[242:245], v[242:245], 0
	v_mfma_f32_16x16x32_bf16 v[112:115], v[242:245], v[242:245], 0
	v_mfma_f32_16x16x32_bf16 v[76:79], v[242:245], v[242:245], 0
	v_mfma_f32_16x16x32_bf16 v[84:87], v[242:245], v[242:245], 0
	v_mfma_f32_16x16x32_bf16 v[148:151], v[242:245], v[242:245], 0
	v_mfma_f32_16x16x32_bf16 v[152:155], v[242:245], v[242:245], 0
	v_mfma_f32_16x16x32_bf16 v[132:135], v[242:245], v[242:245], 0
	v_mfma_f32_16x16x32_bf16 v[136:139], v[242:245], v[242:245], 0
	v_mfma_f32_16x16x32_bf16 v[116:119], v[242:245], v[242:245], 0
	v_mfma_f32_16x16x32_bf16 v[120:123], v[242:245], v[242:245], 0
	v_mfma_f32_16x16x32_bf16 v[96:99], v[242:245], v[242:245], 0
	v_mfma_f32_16x16x32_bf16 v[104:107], v[242:245], v[242:245], 0
	v_mfma_f32_16x16x32_bf16 v[80:83], v[242:245], v[242:245], 0
	v_mfma_f32_16x16x32_bf16 v[88:91], v[242:245], v[242:245], 0
	v_mfma_f32_16x16x32_bf16 v[60:63], v[242:245], v[242:245], 0
	v_mfma_f32_16x16x32_bf16 v[64:67], v[242:245], v[242:245], 0
	v_mfma_f32_16x16x32_bf16 v[44:47], v[242:245], v[242:245], 0
	v_mfma_f32_16x16x32_bf16 v[48:51], v[242:245], v[242:245], 0
	v_mfma_f32_16x16x32_bf16 v[28:31], v[242:245], v[242:245], 0
	v_mfma_f32_16x16x32_bf16 v[32:35], v[242:245], v[242:245], 0
	v_mfma_f32_16x16x32_bf16 v[92:95], v[242:245], v[242:245], 0
	v_mfma_f32_16x16x32_bf16 v[100:103], v[242:245], v[242:245], 0
	v_mfma_f32_16x16x32_bf16 v[68:71], v[242:245], v[242:245], 0
	v_mfma_f32_16x16x32_bf16 v[72:75], v[242:245], v[242:245], 0
	v_mfma_f32_16x16x32_bf16 v[52:55], v[242:245], v[242:245], 0
	v_mfma_f32_16x16x32_bf16 v[56:59], v[242:245], v[242:245], 0
	v_mfma_f32_16x16x32_bf16 v[36:39], v[242:245], v[242:245], 0
	v_mfma_f32_16x16x32_bf16 v[40:43], v[242:245], v[242:245], 0
	s_waitcnt vmcnt(8)
	s_barrier
	v_and_b32_e32 v2, 15, v6
	v_lshlrev_b32_e32 v3, 2, v6
	v_lshl_or_b32 v189, s27, 6, v2
	v_lshl_or_b32 v2, v2, 6, v188
	v_and_b32_e32 v3, 32, v3
	v_bitop3_b32 v4, v2, s12, v3 bitop3:0xde
	v_bitop3_b32 v190, v2, s34, v3 bitop3:0xde
	v_lshlrev_b32_e32 v2, 3, v6
	v_and_b32_e32 v164, 0x1f8, v2
	v_lshlrev_b32_e32 v2, 13, v7
	v_and_b32_e32 v2, 0xffffc000, v2
	v_lshl_add_u32 v2, v8, 10, v2
	v_and_b32_e32 v3, 1, v7
	v_lshl_or_b32 v2, v3, 6, v2
	v_lshl_add_u32 v166, v9, 1, v2
	v_lshlrev_b32_e32 v2, 13, v10
	s_cmpk_lt_u32 s0, 0x100
	v_and_b32_e32 v2, 0xffffc000, v2
	s_waitcnt vmcnt(6)
	s_cselect_b64 s[30:31], -1, 0
	s_lshl_b32 s0, s27, 15
	s_lshl_b32 s1, s1, 13
	v_lshl_add_u32 v2, v11, 10, v2
	v_and_b32_e32 v3, 1, v10
	s_or_b32 s27, s1, s0
	v_lshl_or_b32 v2, v3, 6, v2
	v_readlane_b32 s0, v253, 51
	s_ashr_i32 s46, s27, 31
	v_mov_b32_e32 v165, v27
	v_mov_b32_e32 v167, v27
	v_lshl_add_u32 v176, v12, 1, v2
	v_mov_b32_e32 v177, v27
	s_mov_b64 s[36:37], -1
	v_add_u32_e32 v191, 0, v4
	s_mov_b32 s34, s0
	s_barrier
	s_branch .LBB0_380

.LBB0_489:
	v_mov_b32_e32 v182, v0
	s_barrier
	s_mov_b32 s0, 0x3fffe0
	v_ashrrev_i32_e32 v3, 31, v182
	v_lshrrev_b32_e32 v3, 26, v3
	v_add_u32_e32 v3, v182, v3
	v_ashrrev_i32_e32 v6, 6, v3
	v_bfe_i32 v3, v182, 27, 1
	v_lshlrev_b32_e32 v2, 4, v182
	v_lshrrev_b32_e32 v3, 22, v3
	v_add_u32_e32 v3, v2, v3
	v_and_b32_e32 v3, 0xfffffc00, v3
	v_sub_u32_e32 v3, v2, v3
	v_lshrrev_b32_e32 v4, 4, v3
	v_bitop3_b32 v3, v4, v3, 32 bitop3:0x6c
	v_ashrrev_i32_e32 v5, 31, v3
	v_lshrrev_b32_e32 v5, 26, v5
	v_add_u32_e32 v5, v3, v5
	v_lshlrev_b32_e32 v4, 3, v6
	v_ashrrev_i32_e32 v7, 6, v5
	v_and_b32_e32 v5, 0xc0, v5
	v_and_b32_e32 v4, -16, v4
	v_sub_u32_e32 v3, v3, v5
	v_add_u32_e32 v4, v7, v4
	v_lshlrev_b32_e32 v8, 5, v6
	v_ashrrev_i16_sdwa v3, v225, sext(v3) dst_sel:DWORD dst_unused:UNUSED_PAD src0_sel:DWORD src1_sel:BYTE_0
	v_and_b32_e32 v9, 32, v8
	v_bfe_i32 v8, v3, 0, 16
	v_lshlrev_b32_e32 v3, 1, v4
	v_lshrrev_b32_e32 v5, 2, v4
	v_and_b32_e32 v10, 3, v7
	v_and_b32_e32 v3, 24, v3
	v_and_b32_e32 v5, 4, v5
	v_and_or_b32 v10, v4, s0, v10
	v_or3_b32 v3, v10, v5, v3
	v_add_lshl_u32 v5, v9, v8, 1
	v_add_u32_e32 v2, 0x2000, v2
	v_lshl_add_u32 v26, v3, 10, v5
	v_ashrrev_i32_e32 v3, 31, v2
	v_lshrrev_b32_e32 v3, 22, v3
	v_add_u32_e32 v3, v2, v3
	v_ashrrev_i32_e32 v9, 10, v3
	v_mul_i32_i24_e32 v3, 0x400, v9
	v_sub_u32_e32 v2, v2, v3
	v_lshrrev_b32_e32 v3, 4, v2
	v_bitop3_b32 v2, v3, v2, 32 bitop3:0x6c
	v_lshl_add_u32 v156, v4, 10, v5
	v_ashrrev_i32_e32 v4, 31, v2
	v_lshrrev_b32_e32 v4, 26, v4
	v_add_u32_e32 v4, v2, v4
	v_lshlrev_b32_e32 v3, 3, v9
	v_ashrrev_i32_e32 v10, 6, v4
	v_and_b32_e32 v4, 0xc0, v4
	v_and_b32_e32 v3, -16, v3
	v_sub_u32_e32 v2, v2, v4
	v_add_u32_e32 v3, v10, v3
	v_ashrrev_i16_sdwa v2, v225, sext(v2) dst_sel:DWORD dst_unused:UNUSED_PAD src0_sel:DWORD src1_sel:BYTE_0
	v_lshlrev_b32_e32 v5, 5, v9
	v_bfe_i32 v11, v2, 0, 16
	v_lshlrev_b32_e32 v2, 1, v3
	v_lshrrev_b32_e32 v4, 2, v3
	v_and_b32_e32 v12, 3, v10
	v_and_b32_e32 v5, 32, v5
	v_and_b32_e32 v2, 24, v2
	v_and_b32_e32 v4, 4, v4
	v_and_or_b32 v12, v3, s0, v12
	v_or3_b32 v2, v12, v4, v2
	v_add_lshl_u32 v4, v5, v11, 1
	v_lshl_add_u32 v158, v3, 10, v4
	v_lshl_add_u32 v160, v2, 10, v4
	v_mov_b32_e32 v2, v27
	v_mov_b32_e32 v3, v27
	v_mov_b32_e32 v4, v27
	v_mov_b32_e32 v5, v27
	v_readfirstlane_b32 s8, v182
	s_ashr_i32 s20, s8, 6
	s_ashr_i32 s11, s8, 8
	s_lshl_b32 s16, s20, 10
	v_readlane_b32 s0, v251, 7
	s_add_u32 s21, s60, s0
	s_addc_u32 s22, s61, 0
	s_add_u32 s0, s21, 0x200000
	s_addc_u32 s1, s22, 0
	s_add_i32 s17, s16, 0
	v_mov_b32_e32 v183, 0x7f7f7f7f
	s_add_i32 m0, s17, 0x10000
	v_readlane_b32 s4, v251, 8
	v_readlane_b32 s5, v251, 9
	s_nop 0
	s_nop 0
	s_nop 0
	s_waitcnt lgkmcnt(0)
	s_nop 0
	s_nop 0
	s_nop 0
	s_nop 0
	s_nop 0
	s_nop 0
	s_nop 0
	s_nop 0
	s_nop 0
	s_nop 0
	s_nop 0
	s_nop 0
	s_nop 0
	s_nop 0
	s_nop 0
	s_nop 0
	s_nop 0
	s_nop 0
	s_nop 0
	s_nop 0
	global_load_lds_dwordx4 v26, s[0:1]
	s_add_i32 m0, s17, 0x12000
	s_add_u32 s26, s21, 0x220000
	global_load_lds_dwordx4 v160, s[0:1]
	s_addc_u32 s27, s22, 0
	s_add_i32 m0, s17, 0x14000
	s_add_i32 s22, s17, 0x2000
	global_load_lds_dwordx4 v26, s[26:27]
	s_add_i32 m0, s17, 0x16000
	s_add_i32 s23, s17, 0x4000
	global_load_lds_dwordx4 v160, s[26:27]
	s_mov_b32 m0, s17
	s_add_i32 s26, s17, 0x6000
	global_load_lds_dwordx4 v156, s[84:85]
	s_mov_b32 m0, s22
	global_load_lds_dwordx4 v158, s[84:85]
	s_mov_b32 m0, s23
	s_cmp_lg_u32 s11, 1
	global_load_lds_dwordx4 v156, s[4:5]
	s_mov_b32 m0, s26
	s_nop 0
	global_load_lds_dwordx4 v158, s[4:5]
	s_cbranch_scc1 .LBB0_491
	s_barrier
.LBB0_491:
	v_lshl_add_u64 v[2:3], s[0:1], 0, v[26:27]
	v_mov_b32_e32 v161, v27
	v_and_b32_e32 v16, 15, v182
	v_and_b32_e32 v184, 48, v182
	v_lshlrev_b32_e32 v17, 2, v182
	v_lshl_add_u64 v[4:5], s[0:1], 0, v[160:161]
	v_mov_b32_e32 v157, v27
	s_and_b32 s27, s20, 3
	v_lshl_or_b32 v185, s11, 6, v16
	s_lshl_b32 s12, s11, 13
	v_lshl_or_b32 v16, v16, 6, v184
	v_and_b32_e32 v17, 32, v17
	s_add_i32 m0, s17, 0x18000
	v_lshl_add_u64 v[2:3], v[2:3], 0, s[82:83]
	v_lshl_add_u64 v[12:13], s[84:85], 0, v[156:157]
	v_mov_b32_e32 v159, v27
	v_bitop3_b32 v18, v16, s12, v17 bitop3:0xde
	s_lshl_b32 s12, s27, 12
	global_load_lds_dwordx4 v[2:3], off
	v_lshl_add_u64 v[2:3], v[4:5], 0, s[82:83]
	s_add_i32 m0, s17, 0x1a000
	s_add_i32 s34, s17, 0x8000
	s_add_i32 s35, s17, 0xa000
	v_lshl_add_u64 v[14:15], s[84:85], 0, v[158:159]
	global_load_lds_dwordx4 v[2:3], off
	v_lshl_add_u64 v[2:3], v[12:13], 0, s[82:83]
	s_mov_b32 m0, s34
	s_add_u32 s20, s0, 0x20080
	global_load_lds_dwordx4 v[2:3], off
	v_lshl_add_u64 v[2:3], v[14:15], 0, s[82:83]
	s_mov_b32 m0, s35
	s_addc_u32 s21, s1, 0
	global_load_lds_dwordx4 v[2:3], off
	s_add_i32 m0, s17, 0x1c000
	v_lshl_add_u64 v[2:3], s[20:21], 0, v[26:27]
	global_load_lds_dwordx4 v[2:3], off
	v_lshl_add_u64 v[2:3], s[20:21], 0, v[160:161]
	s_add_i32 m0, s17, 0x1e000
	v_readlane_b32 s4, v251, 61
	global_load_lds_dwordx4 v[2:3], off
	v_mov_b32_e32 v242, 0
	v_mov_b32_e32 v243, 0
	v_mov_b32_e32 v244, 0
	v_mov_b32_e32 v245, 0
	s_nop 1
	v_mfma_f32_16x16x32_bf16 v[144:147], v[242:245], v[242:245], 0
	v_mfma_f32_16x16x32_bf16 v[148:151], v[242:245], v[242:245], 0
	v_mfma_f32_16x16x32_bf16 v[124:127], v[242:245], v[242:245], 0
	v_mfma_f32_16x16x32_bf16 v[128:131], v[242:245], v[242:245], 0
	v_mfma_f32_16x16x32_bf16 v[108:111], v[242:245], v[242:245], 0
	v_mfma_f32_16x16x32_bf16 v[112:115], v[242:245], v[242:245], 0
	v_mfma_f32_16x16x32_bf16 v[92:95], v[242:245], v[242:245], 0
	v_mfma_f32_16x16x32_bf16 v[96:99], v[242:245], v[242:245], 0
	v_mfma_f32_16x16x32_bf16 v[152:155], v[242:245], v[242:245], 0
	v_mfma_f32_16x16x32_bf16 v[140:143], v[242:245], v[242:245], 0
	v_mfma_f32_16x16x32_bf16 v[132:135], v[242:245], v[242:245], 0
	v_mfma_f32_16x16x32_bf16 v[136:139], v[242:245], v[242:245], 0
	v_mfma_f32_16x16x32_bf16 v[116:119], v[242:245], v[242:245], 0
	v_mfma_f32_16x16x32_bf16 v[120:123], v[242:245], v[242:245], 0
	v_mfma_f32_16x16x32_bf16 v[100:103], v[242:245], v[242:245], 0
	v_mfma_f32_16x16x32_bf16 v[104:107], v[242:245], v[242:245], 0
	v_mfma_f32_16x16x32_bf16 v[76:79], v[242:245], v[242:245], 0
	v_mfma_f32_16x16x32_bf16 v[80:83], v[242:245], v[242:245], 0
	v_mfma_f32_16x16x32_bf16 v[60:63], v[242:245], v[242:245], 0
	v_mfma_f32_16x16x32_bf16 v[64:67], v[242:245], v[242:245], 0
	v_mfma_f32_16x16x32_bf16 v[44:47], v[242:245], v[242:245], 0
	v_mfma_f32_16x16x32_bf16 v[48:51], v[242:245], v[242:245], 0
	v_mfma_f32_16x16x32_bf16 v[28:31], v[242:245], v[242:245], 0
	v_mfma_f32_16x16x32_bf16 v[32:35], v[242:245], v[242:245], 0
	v_mfma_f32_16x16x32_bf16 v[84:87], v[242:245], v[242:245], 0
	v_mfma_f32_16x16x32_bf16 v[88:91], v[242:245], v[242:245], 0
	v_mfma_f32_16x16x32_bf16 v[68:71], v[242:245], v[242:245], 0
	v_mfma_f32_16x16x32_bf16 v[72:75], v[242:245], v[242:245], 0
	v_mfma_f32_16x16x32_bf16 v[52:55], v[242:245], v[242:245], 0
	v_mfma_f32_16x16x32_bf16 v[56:59], v[242:245], v[242:245], 0
	v_mfma_f32_16x16x32_bf16 v[40:43], v[242:245], v[242:245], 0
	v_mfma_f32_16x16x32_bf16 v[36:39], v[242:245], v[242:245], 0
	s_waitcnt vmcnt(8)
	s_barrier
	v_lshlrev_b32_e32 v2, 13, v6
	v_and_b32_e32 v2, 0xffffc000, v2
	v_lshl_add_u32 v2, v7, 10, v2
	v_and_b32_e32 v3, 1, v6
	v_lshl_or_b32 v2, v3, 6, v2
	v_lshl_add_u32 v2, v8, 1, v2
	v_mov_b32_e32 v3, v27
	v_readlane_b32 s5, v251, 62
	s_waitcnt vmcnt(6)
	v_bitop3_b32 v186, v16, s12, v17 bitop3:0xde
	s_mov_b32 s36, -2
	v_lshl_add_u64 v[162:163], s[4:5], 0, v[2:3]
	v_lshlrev_b32_e32 v2, 13, v9
	v_and_b32_e32 v2, 0xffffc000, v2
	v_lshl_add_u32 v2, v10, 10, v2
	v_and_b32_e32 v3, 1, v9
	v_lshl_or_b32 v2, v3, 6, v2
	v_lshl_add_u32 v2, v11, 1, v2
	v_mov_b32_e32 v3, v27
	v_lshl_add_u64 v[164:165], s[4:5], 0, v[2:3]
	s_mov_b64 s[20:21], 0xd220080
	v_add_u32_e32 v187, 0, v18
	s_barrier

.LBB0_538:
	v_readlane_b32 s4, v252, 2
	v_readlane_b32 s5, v252, 3
	s_cmp_le_i32 s4, s8
	s_cselect_b64 s[0:1], -1, 0
	s_cmp_lt_i32 s8, s5
	s_cselect_b64 s[16:17], -1, 0
	s_and_b64 s[20:21], s[0:1], s[16:17]
	v_readlane_b32 s0, v251, 15
	v_readlane_b32 s1, v251, 16
	s_andn2_b64 vcc, exec, s[20:21]
	s_nop 0
	v_cndmask_b32_e64 v2, 0, 1, s[0:1]
	v_cmp_ne_u32_e64 s[38:39], 1, v2
	s_cbranch_vccnz .LBB0_619
	s_and_b64 vcc, exec, s[38:39]
	s_and_b64 vcc, exec, s[38:39]
	s_cbranch_vccnz .LBB0_619
	v_mov_b32_e32 v149, v0
	v_mov_b32_e32 v28, v27
	v_ashrrev_i32_e32 v2, 31, v149
	v_lshrrev_b32_e32 v2, 26, v2
	v_add_u32_e32 v2, v149, v2
	v_ashrrev_i32_e32 v148, 6, v2
	v_bfe_i32 v2, v149, 27, 1
	v_lshlrev_b32_e32 v52, 4, v149
	v_lshrrev_b32_e32 v2, 22, v2
	v_add_u32_e32 v2, v52, v2
	v_and_b32_e32 v2, 0xfffffc00, v2
	v_sub_u32_e32 v2, v52, v2
	v_mov_b32_e32 v29, v27
	v_lshrrev_b32_e32 v3, 4, v2
	v_mov_b32_e32 v26, v27
	v_mov_b64_e32 v[130:131], v[28:29]
	v_bitop3_b32 v22, v3, v2, 32 bitop3:0x6c
	v_mov_b64_e32 v[128:129], v[26:27]
	v_ashrrev_i32_e32 v10, 31, v22
	v_lshlrev_b32_e32 v6, 3, v148
	v_lshrrev_b32_e32 v10, 26, v10
	v_and_b32_e32 v14, -16, v6
	v_add_u32_e32 v23, v22, v10
	v_ashrrev_i32_e32 v26, 6, v23
	v_add_u32_e32 v49, v26, v14
	v_lshlrev_b32_e32 v18, 5, v148
	v_and_b32_e32 v23, 0xc0, v23
	v_and_b32_e32 v44, 32, v18
	v_sub_u32_e32 v28, v22, v23
	v_ashrrev_i16_sdwa v28, v225, sext(v28) dst_sel:DWORD dst_unused:UNUSED_PAD src0_sel:DWORD src1_sel:BYTE_0
	v_bfe_i32 v150, v28, 0, 16
	v_lshlrev_b32_e32 v32, 1, v49
	v_add_u32_e32 v64, 0x2000, v52
	v_and_b32_e32 v45, 24, v32
	v_lshrrev_b32_e32 v36, 2, v49
	v_ashrrev_i32_e32 v56, 31, v64
	v_and_b32_e32 v46, 4, v36
	v_and_b32_e32 v40, 3, v26
	s_mov_b32 s4, 0x3fffe0
	v_lshrrev_b32_e32 v56, 22, v56
	v_and_or_b32 v47, v49, s4, v40
	v_add_u32_e32 v60, v64, v56
	v_or3_b32 v50, v47, v46, v45
	v_add_lshl_u32 v48, v44, v150, 1
	s_movk_i32 s5, 0xc00
	v_ashrrev_i32_e32 v151, 10, v60
	s_waitcnt lgkmcnt(0)
	v_mad_u64_u32 v[132:133], s[16:17], v49, s7, v[48:49]
	v_mad_u32_u24 v134, v50, s5, v48
	v_mul_i32_i24_e32 v65, 0x400, v151
	v_sub_u32_e32 v68, v64, v65
	v_lshrrev_b32_e32 v69, 4, v68
	v_bitop3_b32 v88, v69, v68, 32 bitop3:0x6c
	v_ashrrev_i32_e32 v76, 31, v88
	v_lshlrev_b32_e32 v72, 3, v151
	v_lshrrev_b32_e32 v76, 26, v76
	v_and_b32_e32 v80, -16, v72
	v_add_u32_e32 v89, v88, v76
	v_ashrrev_i32_e32 v152, 6, v89
	v_add_u32_e32 v112, v152, v80
	v_lshlrev_b32_e32 v84, 5, v151
	v_and_b32_e32 v89, 0xc0, v89
	v_and_b32_e32 v108, 32, v84
	v_sub_u32_e32 v92, v88, v89
	v_ashrrev_i16_sdwa v92, v225, sext(v92) dst_sel:DWORD dst_unused:UNUSED_PAD src0_sel:DWORD src1_sel:BYTE_0
	v_readlane_b32 s0, v252, 8
	v_bfe_i32 v153, v92, 0, 16
	v_lshlrev_b32_e32 v96, 1, v112
	s_add_u32 s8, s0, s46
	v_readlane_b32 s0, v252, 9
	v_and_b32_e32 v109, 24, v96
	v_lshrrev_b32_e32 v100, 2, v112
	v_and_b32_e32 v104, 3, v152
	s_addc_u32 s11, s0, 0
	v_readfirstlane_b32 s0, v149
	v_and_b32_e32 v110, 4, v100
	v_and_or_b32 v111, v112, s4, v104
	s_ashr_i32 s1, s0, 6
	v_or3_b32 v117, v111, v110, v109
	v_add_lshl_u32 v116, v108, v153, 1
	v_mad_u64_u32 v[136:137], s[16:17], v112, s7, v[116:117]
	s_ashr_i32 s34, s0, 8
	s_mul_i32 s22, s56, 0xc0000
	s_lshl_b32 s15, s1, 10
	s_mul_hi_i32 s16, s56, 0xc0000
	s_add_u32 s58, s8, s22
	v_mad_u32_u24 v138, v117, s5, v116
	s_addc_u32 s59, s11, s16
	s_add_i32 s16, s15, 0
	v_mov_b32_e32 v133, 0x7f7f7f7f
	s_add_i32 m0, s16, 0x10000
	global_load_lds_dwordx4 v134, s[58:59]
	s_add_i32 m0, s16, 0x12000
	s_add_u32 s22, s58, 0x60000
	global_load_lds_dwordx4 v138, s[58:59]
	s_addc_u32 s23, s59, 0
	s_add_i32 m0, s16, 0x14000
	s_mul_i32 s17, s13, 0x2c0000
	global_load_lds_dwordx4 v134, s[22:23]
	s_add_i32 m0, s16, 0x16000
	s_mul_hi_i32 s12, s13, 0x2c0000
	s_add_u32 s54, s19, s17
	s_addc_u32 s55, s25, s12
	s_add_i32 s17, s16, 0x2000
	global_load_lds_dwordx4 v138, s[22:23]
	s_mov_b32 m0, s16
	s_add_u32 s26, s54, 0x160000
	global_load_lds_dwordx4 v132, s[54:55]
	s_mov_b32 m0, s17
	s_addc_u32 s27, s55, 0
	s_add_i32 s22, s16, 0x4000
	global_load_lds_dwordx4 v136, s[54:55]
	s_mov_b32 m0, s22
	s_add_i32 s23, s16, 0x6000
	global_load_lds_dwordx4 v132, s[26:27]
	s_mov_b32 m0, s23
	global_load_lds_dwordx4 v136, s[26:27]
	v_mov_b32_e32 v135, v27
	v_mov_b32_e32 v139, v27
	v_mov_b32_e32 v133, v27
	v_mov_b32_e32 v137, v27
	s_cmp_eq_u32 s34, 1
	s_mov_b32 s88, s75
	v_lshl_add_u64 v[146:147], s[58:59], 0, v[134:135]
	v_lshl_add_u64 v[144:145], s[58:59], 0, v[138:139]
	v_lshl_add_u64 v[140:141], s[54:55], 0, v[132:133]
	s_cselect_b64 s[28:29], -1, 0
	s_cmp_lg_u32 s34, 1
	v_lshl_add_u64 v[142:143], s[54:55], 0, v[136:137]
	s_cbranch_scc1 .LBB0_542
	s_barrier
.LBB0_542:
	s_and_b32 s1, s1, 3
	s_add_i32 m0, s16, 0x18000
	v_lshl_add_u64 v[146:147], v[146:147], 0, s[82:83]
	s_lshl_b32 s12, s34, 13
	s_lshl_b32 s35, s1, 12
	global_load_lds_dwordx4 v[146:147], off
	v_lshl_add_u64 v[144:145], v[144:145], 0, s[82:83]
	s_add_i32 m0, s16, 0x1a000
	s_add_i32 s26, s16, 0x8000
	s_add_i32 s27, s16, 0xa000
	global_load_lds_dwordx4 v[144:145], off
	v_lshl_add_u64 v[140:141], v[140:141], 0, s[82:83]
	s_mov_b32 m0, s26
	s_add_u32 s30, s58, 0x60080
	global_load_lds_dwordx4 v[140:141], off
	v_lshl_add_u64 v[140:141], v[142:143], 0, s[82:83]
	s_mov_b32 m0, s27
	s_addc_u32 s31, s59, 0
	global_load_lds_dwordx4 v[140:141], off
	s_add_i32 m0, s16, 0x1c000
	v_lshl_add_u64 v[140:141], s[30:31], 0, v[134:135]
	global_load_lds_dwordx4 v[140:141], off
	v_lshl_add_u64 v[140:141], s[30:31], 0, v[138:139]
	s_add_i32 m0, s16, 0x1e000
	v_lshlrev_b32_e32 v144, 2, v149
	global_load_lds_dwordx4 v[140:141], off
	v_mov_b32_e32 v242, 0
	v_mov_b32_e32 v243, 0
	v_mov_b32_e32 v244, 0
	v_mov_b32_e32 v245, 0
	s_nop 1
	v_mfma_f32_16x16x32_bf16 v[2:5], v[242:245], v[242:245], 0
	v_mfma_f32_16x16x32_bf16 v[6:9], v[242:245], v[242:245], 0
	v_mfma_f32_16x16x32_bf16 v[10:13], v[242:245], v[242:245], 0
	v_mfma_f32_16x16x32_bf16 v[14:17], v[242:245], v[242:245], 0
	v_mfma_f32_16x16x32_bf16 v[18:21], v[242:245], v[242:245], 0
	v_mfma_f32_16x16x32_bf16 v[22:25], v[242:245], v[242:245], 0
	v_mfma_f32_16x16x32_bf16 v[28:31], v[242:245], v[242:245], 0
	v_mfma_f32_16x16x32_bf16 v[32:35], v[242:245], v[242:245], 0
	v_mfma_f32_16x16x32_bf16 v[36:39], v[242:245], v[242:245], 0
	v_mfma_f32_16x16x32_bf16 v[40:43], v[242:245], v[242:245], 0
	v_mfma_f32_16x16x32_bf16 v[44:47], v[242:245], v[242:245], 0
	v_mfma_f32_16x16x32_bf16 v[48:51], v[242:245], v[242:245], 0
	v_mfma_f32_16x16x32_bf16 v[52:55], v[242:245], v[242:245], 0
	v_mfma_f32_16x16x32_bf16 v[56:59], v[242:245], v[242:245], 0
	v_mfma_f32_16x16x32_bf16 v[60:63], v[242:245], v[242:245], 0
	v_mfma_f32_16x16x32_bf16 v[64:67], v[242:245], v[242:245], 0
	v_mfma_f32_16x16x32_bf16 v[68:71], v[242:245], v[242:245], 0
	v_mfma_f32_16x16x32_bf16 v[72:75], v[242:245], v[242:245], 0
	v_mfma_f32_16x16x32_bf16 v[76:79], v[242:245], v[242:245], 0
	v_mfma_f32_16x16x32_bf16 v[80:83], v[242:245], v[242:245], 0
	v_mfma_f32_16x16x32_bf16 v[84:87], v[242:245], v[242:245], 0
	v_mfma_f32_16x16x32_bf16 v[88:91], v[242:245], v[242:245], 0
	v_mfma_f32_16x16x32_bf16 v[92:95], v[242:245], v[242:245], 0
	v_mfma_f32_16x16x32_bf16 v[96:99], v[242:245], v[242:245], 0
	v_mfma_f32_16x16x32_bf16 v[100:103], v[242:245], v[242:245], 0
	v_mfma_f32_16x16x32_bf16 v[104:107], v[242:245], v[242:245], 0
	v_mfma_f32_16x16x32_bf16 v[108:111], v[242:245], v[242:245], 0
	v_mfma_f32_16x16x32_bf16 v[112:115], v[242:245], v[242:245], 0
	v_mfma_f32_16x16x32_bf16 v[116:119], v[242:245], v[242:245], 0
	v_mfma_f32_16x16x32_bf16 v[120:123], v[242:245], v[242:245], 0
	v_mfma_f32_16x16x32_bf16 v[124:127], v[242:245], v[242:245], 0
	v_mfma_f32_16x16x32_bf16 v[128:131], v[242:245], v[242:245], 0
	s_waitcnt vmcnt(8)
	s_barrier
	v_bfe_u32 v141, v149, 4, 2
	v_and_b32_e32 v140, 15, v149
	v_lshlrev_b32_e32 v142, 4, v141
	v_lshl_or_b32 v143, v140, 6, v142
	v_and_b32_e32 v144, 32, v144
	s_cmpk_lt_u32 s0, 0x100
	v_bitop3_b32 v146, v143, s12, v144 bitop3:0xde
	s_cselect_b64 s[30:31], -1, 0
	s_lshl_b32 s0, s34, 15
	s_lshl_b32 s12, s1, 13
	v_lshl_or_b32 v228, s1, 6, v142
	v_lshrrev_b32_e32 v142, 1, v148
	v_mul_lo_u32 v26, v26, s7
	s_mov_b32 s4, 0x2c000
	v_bitop3_b32 v227, v143, s35, v144 bitop3:0xde
	s_or_b32 s46, s12, s0
	v_mad_u64_u32 v[142:143], s[0:1], v142, s4, v[26:27]
	v_and_b32_e32 v26, 1, v148
	v_lshl_or_b32 v26, v26, 6, v142
	v_lshl_add_u32 v142, v150, 1, v26
	v_lshrrev_b32_e32 v144, 1, v151
	v_mul_lo_u32 v26, v152, s7
	s_waitcnt vmcnt(6)
	v_mad_u64_u32 v[144:145], s[0:1], v144, s4, v[26:27]
	v_and_b32_e32 v26, 1, v151
	v_lshl_or_b32 v226, s34, 6, v140
	v_lshlrev_b32_e32 v140, 3, v140
	v_lshl_or_b32 v26, v26, 6, v144
	s_ashr_i32 s47, s46, 31
	v_lshl_or_b32 v140, v141, 7, v140
	v_mov_b32_e32 v141, v27
	s_mul_hi_i32 s68, s13, 0x160000
	s_mul_i32 s74, s13, 0x160000
	s_mul_hi_i32 s75, s56, 0x60000
	s_mul_i32 s76, s56, 0x60000
	v_mov_b32_e32 v143, v27
	v_lshl_add_u32 v144, v153, 1, v26
	v_mov_b32_e32 v145, v27
	s_mov_b32 s0, 0
	v_add_u32_e32 v229, 0, v146
	s_mov_b32 s79, 0
	s_barrier
	s_branch .LBB0_545

.LBB0_665:
	s_and_b64 vcc, exec, s[38:39]
	s_cbranch_vccnz .LBB0_720
	v_ashrrev_i32_e32 v2, 31, v140
	v_lshrrev_b32_e32 v2, 26, v2
	v_add_u32_e32 v2, v140, v2
	v_ashrrev_i32_e32 v141, 6, v2
	v_bfe_i32 v2, v140, 27, 1
	v_lshlrev_b32_e32 v60, 4, v140
	v_lshrrev_b32_e32 v2, 22, v2
	v_add_u32_e32 v2, v60, v2
	v_mov_b32_e32 v28, v27
	v_mov_b32_e32 v29, v27
	v_and_b32_e32 v6, 0xfffffc00, v2
	v_mov_b32_e32 v26, v27
	v_mov_b64_e32 v[130:131], v[28:29]
	v_mov_b64_e32 v[128:129], v[26:27]
	v_sub_u32_e32 v10, v60, v6
	v_lshrrev_b32_e32 v11, 4, v10
	v_bitop3_b32 v32, v11, v10, 32 bitop3:0x6c
	v_ashrrev_i32_e32 v18, 31, v32
	v_lshlrev_b32_e32 v14, 3, v141
	v_lshrrev_b32_e32 v18, 26, v18
	v_and_b32_e32 v22, -16, v14
	v_add_u32_e32 v33, v32, v18
	v_ashrrev_i32_e32 v26, 6, v33
	v_add_u32_e32 v57, v26, v22
	v_lshlrev_b32_e32 v28, 5, v141
	v_and_b32_e32 v33, 0xc0, v33
	v_and_b32_e32 v52, 32, v28
	v_sub_u32_e32 v36, v32, v33
	v_ashrrev_i16_sdwa v36, v225, sext(v36) dst_sel:DWORD dst_unused:UNUSED_PAD src0_sel:DWORD src1_sel:BYTE_0
	v_bfe_i32 v142, v36, 0, 16
	v_lshlrev_b32_e32 v40, 1, v57
	v_add_u32_e32 v72, 0x2000, v60
	v_and_b32_e32 v53, 24, v40
	v_lshrrev_b32_e32 v44, 2, v57
	v_ashrrev_i32_e32 v64, 31, v72
	v_and_b32_e32 v54, 4, v44
	v_and_b32_e32 v48, 3, v26
	s_mov_b32 s5, 0x1fffe0
	v_lshrrev_b32_e32 v64, 22, v64
	v_and_or_b32 v55, v57, s5, v48
	v_add_u32_e32 v68, v72, v64
	v_or3_b32 v58, v55, v54, v53
	v_add_lshl_u32 v56, v52, v142, 1
	v_ashrrev_i32_e32 v143, 10, v68
	v_mad_u64_u32 v[176:177], s[16:17], v57, s7, v[56:57]
	v_lshl_add_u32 v178, v58, 11, v56
	v_mul_i32_i24_e32 v73, 0x400, v143
	v_sub_u32_e32 v76, v72, v73
	v_lshrrev_b32_e32 v77, 4, v76
	v_bitop3_b32 v96, v77, v76, 32 bitop3:0x6c
	v_ashrrev_i32_e32 v84, 31, v96
	v_lshlrev_b32_e32 v80, 3, v143
	v_lshrrev_b32_e32 v84, 26, v84
	v_and_b32_e32 v88, -16, v80
	v_add_u32_e32 v97, v96, v84
	v_ashrrev_i32_e32 v144, 6, v97
	v_add_u32_e32 v121, v144, v88
	v_lshlrev_b32_e32 v92, 5, v143
	v_and_b32_e32 v97, 0xc0, v97
	v_and_b32_e32 v116, 32, v92
	v_sub_u32_e32 v100, v96, v97
	v_ashrrev_i16_sdwa v100, v225, sext(v100) dst_sel:DWORD dst_unused:UNUSED_PAD src0_sel:DWORD src1_sel:BYTE_0
	v_bfe_i32 v145, v100, 0, 16
	v_lshlrev_b32_e32 v104, 1, v121
	v_and_b32_e32 v117, 24, v104
	v_lshrrev_b32_e32 v108, 2, v121
	s_ashr_i32 s1, s0, 6
	v_and_b32_e32 v118, 4, v108
	v_and_b32_e32 v112, 3, v144
	v_and_or_b32 v119, v121, s5, v112
	s_lshl_b32 s8, s1, 10
	v_or3_b32 v122, v119, v118, v117
	v_add_lshl_u32 v120, v116, v145, 1
	s_add_i32 s11, s8, 0
	v_mad_u64_u32 v[180:181], s[16:17], v121, s7, v[120:121]
	v_lshl_add_u32 v182, v122, 11, v120
	s_waitcnt lgkmcnt(0)
	v_mov_b32_e32 v132, 0x7f7f7f7f
	s_add_i32 m0, s11, 0x10000
	s_ashr_i32 s30, s0, 8
	global_load_lds_dwordx4 v178, s[74:75]
	s_add_i32 m0, s11, 0x12000
	s_add_u32 s16, s74, 0x40000
	global_load_lds_dwordx4 v182, s[74:75]
	s_addc_u32 s17, s75, 0
	s_add_i32 m0, s11, 0x14000
	global_load_lds_dwordx4 v178, s[16:17]
	s_add_i32 m0, s11, 0x16000
	v_mov_b32_e32 v179, v27
	global_load_lds_dwordx4 v182, s[16:17]
	s_add_i32 s16, s11, 0x2000
	s_mov_b32 m0, s11
	s_add_u32 s20, s86, 0x160000
	global_load_lds_dwordx4 v176, s[86:87]
	s_mov_b32 m0, s16
	s_addc_u32 s21, s87, 0
	s_add_i32 s17, s11, 0x4000
	global_load_lds_dwordx4 v180, s[86:87]
	s_mov_b32 m0, s17
	s_add_i32 s22, s11, 0x6000
	global_load_lds_dwordx4 v176, s[20:21]
	s_mov_b32 m0, s22
	v_mov_b32_e32 v183, v27
	global_load_lds_dwordx4 v180, s[20:21]
	v_mov_b32_e32 v177, v27
	v_mov_b32_e32 v181, v27
	s_cmp_eq_u32 s30, 1
	v_lshl_add_u64 v[138:139], s[74:75], 0, v[178:179]
	v_lshl_add_u64 v[136:137], s[74:75], 0, v[182:183]
	v_lshl_add_u64 v[132:133], s[86:87], 0, v[176:177]
	s_cselect_b64 s[20:21], -1, 0
	s_cmp_lg_u32 s30, 1
	v_lshl_add_u64 v[134:135], s[86:87], 0, v[180:181]
	s_mov_b32 s81, 0xb0000
	s_cbranch_scc1 .LBB0_668
	s_barrier
.LBB0_668:
	s_and_b32 s12, s1, 3
	s_add_i32 m0, s11, 0x18000
	v_lshl_add_u64 v[138:139], v[138:139], 0, s[82:83]
	s_lshl_b32 s1, s30, 13
	s_lshl_b32 s31, s12, 12
	global_load_lds_dwordx4 v[138:139], off
	v_lshl_add_u64 v[136:137], v[136:137], 0, s[82:83]
	s_add_i32 m0, s11, 0x1a000
	s_add_i32 s46, s11, 0x8000
	s_add_i32 s47, s11, 0xa000
	global_load_lds_dwordx4 v[136:137], off
	v_lshl_add_u64 v[132:133], v[132:133], 0, s[82:83]
	s_mov_b32 m0, s46
	s_add_u32 s26, s74, 0x40080
	global_load_lds_dwordx4 v[132:133], off
	v_lshl_add_u64 v[132:133], v[134:135], 0, s[82:83]
	s_mov_b32 m0, s47
	s_addc_u32 s27, s75, 0
	global_load_lds_dwordx4 v[132:133], off
	s_add_i32 m0, s11, 0x1c000
	v_lshl_add_u64 v[132:133], s[26:27], 0, v[178:179]
	global_load_lds_dwordx4 v[132:133], off
	v_lshl_add_u64 v[132:133], s[26:27], 0, v[182:183]
	s_add_i32 m0, s11, 0x1e000
	v_lshlrev_b32_e32 v135, 2, v140
	global_load_lds_dwordx4 v[132:133], off
	v_mov_b32_e32 v242, 0
	v_mov_b32_e32 v243, 0
	v_mov_b32_e32 v244, 0
	v_mov_b32_e32 v245, 0
	s_nop 1
	v_mfma_f32_16x16x32_bf16 v[2:5], v[242:245], v[242:245], 0
	v_mfma_f32_16x16x32_bf16 v[6:9], v[242:245], v[242:245], 0
	v_mfma_f32_16x16x32_bf16 v[10:13], v[242:245], v[242:245], 0
	v_mfma_f32_16x16x32_bf16 v[14:17], v[242:245], v[242:245], 0
	v_mfma_f32_16x16x32_bf16 v[18:21], v[242:245], v[242:245], 0
	v_mfma_f32_16x16x32_bf16 v[22:25], v[242:245], v[242:245], 0
	v_mfma_f32_16x16x32_bf16 v[28:31], v[242:245], v[242:245], 0
	v_mfma_f32_16x16x32_bf16 v[32:35], v[242:245], v[242:245], 0
	v_mfma_f32_16x16x32_bf16 v[36:39], v[242:245], v[242:245], 0
	v_mfma_f32_16x16x32_bf16 v[40:43], v[242:245], v[242:245], 0
	v_mfma_f32_16x16x32_bf16 v[44:47], v[242:245], v[242:245], 0
	v_mfma_f32_16x16x32_bf16 v[48:51], v[242:245], v[242:245], 0
	v_mfma_f32_16x16x32_bf16 v[52:55], v[242:245], v[242:245], 0
	v_mfma_f32_16x16x32_bf16 v[56:59], v[242:245], v[242:245], 0
	v_mfma_f32_16x16x32_bf16 v[60:63], v[242:245], v[242:245], 0
	v_mfma_f32_16x16x32_bf16 v[64:67], v[242:245], v[242:245], 0
	v_mfma_f32_16x16x32_bf16 v[68:71], v[242:245], v[242:245], 0
	v_mfma_f32_16x16x32_bf16 v[72:75], v[242:245], v[242:245], 0
	v_mfma_f32_16x16x32_bf16 v[76:79], v[242:245], v[242:245], 0
	v_mfma_f32_16x16x32_bf16 v[80:83], v[242:245], v[242:245], 0
	v_mfma_f32_16x16x32_bf16 v[84:87], v[242:245], v[242:245], 0
	v_mfma_f32_16x16x32_bf16 v[88:91], v[242:245], v[242:245], 0
	v_mfma_f32_16x16x32_bf16 v[92:95], v[242:245], v[242:245], 0
	v_mfma_f32_16x16x32_bf16 v[96:99], v[242:245], v[242:245], 0
	v_mfma_f32_16x16x32_bf16 v[100:103], v[242:245], v[242:245], 0
	v_mfma_f32_16x16x32_bf16 v[104:107], v[242:245], v[242:245], 0
	v_mfma_f32_16x16x32_bf16 v[108:111], v[242:245], v[242:245], 0
	v_mfma_f32_16x16x32_bf16 v[112:115], v[242:245], v[242:245], 0
	v_mfma_f32_16x16x32_bf16 v[116:119], v[242:245], v[242:245], 0
	v_mfma_f32_16x16x32_bf16 v[120:123], v[242:245], v[242:245], 0
	v_mfma_f32_16x16x32_bf16 v[124:127], v[242:245], v[242:245], 0
	v_mfma_f32_16x16x32_bf16 v[128:131], v[242:245], v[242:245], 0
	s_waitcnt vmcnt(8)
	s_barrier
	v_bfe_u32 v133, v140, 4, 2
	v_and_b32_e32 v132, 15, v140
	v_lshlrev_b32_e32 v201, 4, v133
	v_lshl_or_b32 v200, s30, 6, v132
	v_lshl_or_b32 v132, v132, 6, v201
	v_and_b32_e32 v135, 32, v135
	v_bitop3_b32 v136, v132, s1, v135 bitop3:0xde
	v_bitop3_b32 v202, v132, s31, v135 bitop3:0xde
	v_lshrrev_b32_e32 v132, 1, v141
	v_mul_lo_u32 v26, v26, s7
	s_mov_b32 s5, 0x2c000
	v_lshlrev_b32_e32 v134, 3, v133
	s_cmpk_lt_u32 s0, 0x100
	v_cmp_eq_u32_e64 s[0:1], 0, v133
	v_mad_u64_u32 v[132:133], s[34:35], v132, s5, v[26:27]
	v_and_b32_e32 v26, 1, v141
	v_lshl_or_b32 v26, v26, 6, v132
	v_lshl_add_u32 v188, v142, 1, v26
	v_lshrrev_b32_e32 v132, 1, v143
	v_mul_lo_u32 v26, v144, s7
	s_waitcnt vmcnt(6)
	s_cselect_b64 s[26:27], -1, 0
	v_lshl_or_b32 v203, s12, 5, v134
	s_or_b32 s30, s12, s30
	v_mad_u64_u32 v[132:133], s[34:35], v132, s5, v[26:27]
	v_and_b32_e32 v26, 1, v143
	s_cmp_eq_u32 s30, 0
	v_lshlrev_b32_e32 v184, 2, v203
	v_mov_b32_e32 v185, v27
	v_lshl_or_b32 v26, v26, 6, v132
	s_mov_b32 s57, 0
	s_cselect_b64 s[30:31], -1, 0
	v_lshl_add_u64 v[186:187], s[48:49], 0, v[184:185]
	v_mov_b32_e32 v189, v27
	v_lshl_add_u32 v190, v145, 1, v26
	v_mov_b32_e32 v191, v27
	v_add_u32_e32 v185, 0, v136
	s_lshl_b32 s68, s12, 2
	s_barrier
	s_branch .LBB0_671

.LBB0_724:
	s_and_b64 vcc, exec, s[38:39]
	s_cbranch_vccnz .LBB0_760
	v_ashrrev_i32_e32 v2, 31, v140
	v_lshrrev_b32_e32 v2, 26, v2
	v_add_u32_e32 v2, v140, v2
	v_ashrrev_i32_e32 v141, 6, v2
	v_bfe_i32 v2, v140, 27, 1
	v_lshlrev_b32_e32 v60, 4, v140
	v_lshrrev_b32_e32 v2, 22, v2
	v_add_u32_e32 v2, v60, v2
	v_mov_b32_e32 v28, v27
	v_mov_b32_e32 v29, v27
	v_and_b32_e32 v6, 0xfffffc00, v2
	v_mov_b32_e32 v26, v27
	v_mov_b64_e32 v[130:131], v[28:29]
	v_mov_b64_e32 v[128:129], v[26:27]
	v_sub_u32_e32 v10, v60, v6
	v_lshrrev_b32_e32 v11, 4, v10
	v_bitop3_b32 v32, v11, v10, 32 bitop3:0x6c
	v_ashrrev_i32_e32 v18, 31, v32
	v_lshlrev_b32_e32 v14, 3, v141
	v_lshrrev_b32_e32 v18, 26, v18
	v_and_b32_e32 v22, -16, v14
	v_add_u32_e32 v33, v32, v18
	v_ashrrev_i32_e32 v26, 6, v33
	v_add_u32_e32 v57, v26, v22
	v_lshlrev_b32_e32 v28, 5, v141
	v_and_b32_e32 v33, 0xc0, v33
	v_and_b32_e32 v52, 32, v28
	v_sub_u32_e32 v36, v32, v33
	v_ashrrev_i16_sdwa v36, v225, sext(v36) dst_sel:DWORD dst_unused:UNUSED_PAD src0_sel:DWORD src1_sel:BYTE_0
	v_bfe_i32 v142, v36, 0, 16
	v_lshlrev_b32_e32 v40, 1, v57
	v_add_u32_e32 v72, 0x2000, v60
	v_and_b32_e32 v53, 24, v40
	v_lshrrev_b32_e32 v44, 2, v57
	v_ashrrev_i32_e32 v64, 31, v72
	v_and_b32_e32 v54, 4, v44
	v_and_b32_e32 v48, 3, v26
	s_mov_b32 s4, 0x1fffe0
	v_lshrrev_b32_e32 v64, 22, v64
	v_and_or_b32 v55, v57, s4, v48
	v_add_u32_e32 v68, v72, v64
	v_or3_b32 v58, v55, v54, v53
	v_add_lshl_u32 v56, v52, v142, 1
	v_ashrrev_i32_e32 v143, 10, v68
	v_mad_u64_u32 v[144:145], s[16:17], v57, s7, v[56:57]
	v_lshl_add_u32 v146, v58, 11, v56
	v_mul_i32_i24_e32 v73, 0x400, v143
	v_sub_u32_e32 v76, v72, v73
	v_lshrrev_b32_e32 v77, 4, v76
	v_bitop3_b32 v96, v77, v76, 32 bitop3:0x6c
	v_ashrrev_i32_e32 v84, 31, v96
	v_lshlrev_b32_e32 v80, 3, v143
	v_lshrrev_b32_e32 v84, 26, v84
	v_and_b32_e32 v88, -16, v80
	v_add_u32_e32 v97, v96, v84
	v_ashrrev_i32_e32 v154, 6, v97
	v_add_u32_e32 v121, v154, v88
	v_lshlrev_b32_e32 v92, 5, v143
	v_and_b32_e32 v97, 0xc0, v97
	v_and_b32_e32 v116, 32, v92
	v_sub_u32_e32 v100, v96, v97
	v_ashrrev_i16_sdwa v100, v225, sext(v100) dst_sel:DWORD dst_unused:UNUSED_PAD src0_sel:DWORD src1_sel:BYTE_0
	v_bfe_i32 v155, v100, 0, 16
	v_lshlrev_b32_e32 v104, 1, v121
	v_and_b32_e32 v117, 24, v104
	v_lshrrev_b32_e32 v108, 2, v121
	s_ashr_i32 s1, s0, 6
	v_and_b32_e32 v118, 4, v108
	v_and_b32_e32 v112, 3, v154
	v_and_or_b32 v119, v121, s4, v112
	s_lshl_b32 s8, s1, 10
	v_or3_b32 v122, v119, v118, v117
	v_add_lshl_u32 v120, v116, v155, 1
	s_add_i32 s11, s8, 0
	v_mad_u64_u32 v[148:149], s[16:17], v121, s7, v[120:121]
	v_lshl_add_u32 v150, v122, 11, v120
	s_waitcnt lgkmcnt(0)
	v_mov_b32_e32 v132, 0x7f7f7f7f
	s_add_i32 m0, s11, 0x10000
	s_ashr_i32 s26, s0, 8
	global_load_lds_dwordx4 v146, s[58:59]
	s_add_i32 m0, s11, 0x12000
	s_add_u32 s16, s58, 0x40000
	global_load_lds_dwordx4 v150, s[58:59]
	s_addc_u32 s17, s59, 0
	s_add_i32 m0, s11, 0x14000
	global_load_lds_dwordx4 v146, s[16:17]
	s_add_i32 m0, s11, 0x16000
	v_mov_b32_e32 v147, v27
	global_load_lds_dwordx4 v150, s[16:17]
	s_add_i32 s16, s11, 0x2000
	s_mov_b32 m0, s11
	s_add_u32 s20, s60, 0x160000
	global_load_lds_dwordx4 v144, s[60:61]
	s_mov_b32 m0, s16
	s_addc_u32 s21, s61, 0
	s_add_i32 s17, s11, 0x4000
	global_load_lds_dwordx4 v148, s[60:61]
	s_mov_b32 m0, s17
	s_add_i32 s22, s11, 0x6000
	global_load_lds_dwordx4 v144, s[20:21]
	s_mov_b32 m0, s22
	v_mov_b32_e32 v151, v27
	global_load_lds_dwordx4 v148, s[20:21]
	v_mov_b32_e32 v145, v27
	v_mov_b32_e32 v149, v27
	s_cmp_eq_u32 s26, 1
	v_lshl_add_u64 v[138:139], s[58:59], 0, v[146:147]
	v_lshl_add_u64 v[136:137], s[58:59], 0, v[150:151]
	v_lshl_add_u64 v[132:133], s[60:61], 0, v[144:145]
	s_cselect_b64 s[20:21], -1, 0
	s_cmp_lg_u32 s26, 1
	v_lshl_add_u64 v[134:135], s[60:61], 0, v[148:149]
	s_cbranch_scc1 .LBB0_727
	s_barrier
.LBB0_727:
	s_and_b32 s12, s1, 3
	s_add_i32 m0, s11, 0x18000
	v_lshl_add_u64 v[138:139], v[138:139], 0, s[82:83]
	s_lshl_b32 s1, s26, 13
	s_lshl_b32 s27, s12, 12
	global_load_lds_dwordx4 v[138:139], off
	v_lshl_add_u64 v[136:137], v[136:137], 0, s[82:83]
	s_add_i32 m0, s11, 0x1a000
	s_add_i32 s46, s11, 0x8000
	s_add_i32 s47, s11, 0xa000
	global_load_lds_dwordx4 v[136:137], off
	v_lshl_add_u64 v[132:133], v[132:133], 0, s[82:83]
	s_mov_b32 m0, s46
	s_add_u32 s30, s58, 0x40080
	global_load_lds_dwordx4 v[132:133], off
	v_lshl_add_u64 v[132:133], v[134:135], 0, s[82:83]
	s_mov_b32 m0, s47
	s_addc_u32 s31, s59, 0
	global_load_lds_dwordx4 v[132:133], off
	s_add_i32 m0, s11, 0x1c000
	v_lshl_add_u64 v[132:133], s[30:31], 0, v[146:147]
	global_load_lds_dwordx4 v[132:133], off
	v_lshl_add_u64 v[132:133], s[30:31], 0, v[150:151]
	s_add_i32 m0, s11, 0x1e000
	v_mul_lo_u32 v26, v26, s7
	global_load_lds_dwordx4 v[132:133], off
	v_mov_b32_e32 v242, 0
	v_mov_b32_e32 v243, 0
	v_mov_b32_e32 v244, 0
	v_mov_b32_e32 v245, 0
	s_nop 1
	v_mfma_f32_16x16x32_bf16 v[2:5], v[242:245], v[242:245], 0
	v_mfma_f32_16x16x32_bf16 v[6:9], v[242:245], v[242:245], 0
	v_mfma_f32_16x16x32_bf16 v[10:13], v[242:245], v[242:245], 0
	v_mfma_f32_16x16x32_bf16 v[14:17], v[242:245], v[242:245], 0
	v_mfma_f32_16x16x32_bf16 v[18:21], v[242:245], v[242:245], 0
	v_mfma_f32_16x16x32_bf16 v[22:25], v[242:245], v[242:245], 0
	v_mfma_f32_16x16x32_bf16 v[28:31], v[242:245], v[242:245], 0
	v_mfma_f32_16x16x32_bf16 v[32:35], v[242:245], v[242:245], 0
	v_mfma_f32_16x16x32_bf16 v[36:39], v[242:245], v[242:245], 0
	v_mfma_f32_16x16x32_bf16 v[40:43], v[242:245], v[242:245], 0
	v_mfma_f32_16x16x32_bf16 v[44:47], v[242:245], v[242:245], 0
	v_mfma_f32_16x16x32_bf16 v[48:51], v[242:245], v[242:245], 0
	v_mfma_f32_16x16x32_bf16 v[52:55], v[242:245], v[242:245], 0
	v_mfma_f32_16x16x32_bf16 v[56:59], v[242:245], v[242:245], 0
	v_mfma_f32_16x16x32_bf16 v[60:63], v[242:245], v[242:245], 0
	v_mfma_f32_16x16x32_bf16 v[64:67], v[242:245], v[242:245], 0
	v_mfma_f32_16x16x32_bf16 v[68:71], v[242:245], v[242:245], 0
	v_mfma_f32_16x16x32_bf16 v[72:75], v[242:245], v[242:245], 0
	v_mfma_f32_16x16x32_bf16 v[76:79], v[242:245], v[242:245], 0
	v_mfma_f32_16x16x32_bf16 v[80:83], v[242:245], v[242:245], 0
	v_mfma_f32_16x16x32_bf16 v[84:87], v[242:245], v[242:245], 0
	v_mfma_f32_16x16x32_bf16 v[88:91], v[242:245], v[242:245], 0
	v_mfma_f32_16x16x32_bf16 v[92:95], v[242:245], v[242:245], 0
	v_mfma_f32_16x16x32_bf16 v[96:99], v[242:245], v[242:245], 0
	v_mfma_f32_16x16x32_bf16 v[100:103], v[242:245], v[242:245], 0
	v_mfma_f32_16x16x32_bf16 v[104:107], v[242:245], v[242:245], 0
	v_mfma_f32_16x16x32_bf16 v[108:111], v[242:245], v[242:245], 0
	v_mfma_f32_16x16x32_bf16 v[112:115], v[242:245], v[242:245], 0
	v_mfma_f32_16x16x32_bf16 v[116:119], v[242:245], v[242:245], 0
	v_mfma_f32_16x16x32_bf16 v[120:123], v[242:245], v[242:245], 0
	v_mfma_f32_16x16x32_bf16 v[124:127], v[242:245], v[242:245], 0
	v_mfma_f32_16x16x32_bf16 v[128:131], v[242:245], v[242:245], 0
	s_waitcnt vmcnt(8)
	s_barrier
	v_bfe_u32 v133, v140, 4, 2
	v_and_b32_e32 v132, 15, v140
	v_lshlrev_b32_e32 v135, 4, v133
	v_lshl_or_b32 v164, s26, 6, v132
	v_lshl_or_b32 v132, v132, 6, v135
	v_lshlrev_b32_e32 v135, 2, v140
	v_and_b32_e32 v135, 32, v135
	v_bitop3_b32 v136, v132, s1, v135 bitop3:0xde
	v_bitop3_b32 v165, v132, s27, v135 bitop3:0xde
	v_lshrrev_b32_e32 v132, 1, v141
	s_mov_b32 s4, 0x2c000
	v_lshlrev_b32_e32 v134, 3, v133
	s_cmpk_lt_u32 s0, 0x100
	v_cmp_eq_u32_e64 s[0:1], 0, v133
	v_mad_u64_u32 v[132:133], s[30:31], v132, s4, v[26:27]
	v_and_b32_e32 v26, 1, v141
	v_lshl_or_b32 v26, v26, 6, v132
	v_lshl_add_u32 v152, v142, 1, v26
	v_lshrrev_b32_e32 v132, 1, v143
	v_mul_lo_u32 v26, v154, s7
	s_waitcnt vmcnt(6)
	v_mad_u64_u32 v[132:133], s[30:31], v132, s4, v[26:27]
	v_and_b32_e32 v26, 1, v143
	v_lshl_or_b32 v26, v26, 6, v132
	s_cselect_b64 s[26:27], -1, 0
	v_lshl_or_b32 v166, s12, 5, v134
	s_mov_b32 s57, 0
	v_mov_b32_e32 v153, v27
	v_lshl_add_u32 v154, v155, 1, v26
	v_mov_b32_e32 v155, v27
	v_add_u32_e32 v167, 0, v136
	s_lshl_b32 s68, s12, 2
	s_barrier
	s_branch .LBB0_730
